# v98 with the one-time group start offsets halved (96 / 190 sleep units)
# speedup vs baseline: 1.0050x; 1.0050x over previous
; #define SW_BEGIN(id) unsigned long long sw_t0_##id = 0; if (SW_ID == (id)) sw_t0_##id = __builtin_amdgcn_s_memrealtime()
; #define SW_BEGIN(id) do {} while (0)
; #define GAS __attribute__((address_space(1)))
; __global__ void __launch_bounds__(NWAVES * 64, 2) hybrid_fwd(Args args) {
;     ...
;             pg8::Gemm g{(const f16*)XB, (const f16*)WIN + (size_t)l * PW * DM, MROWS, PW, DM}; pg8::StaticOrder S; S.init(MROWS, PW, G, bx, G1_CPERM, cls ? 1 : 0);
;             pg8::EpiProj E{PROJ, PROJ + (size_t)MROWS * KVW, PART, (const GAS float*)q_norm_g + l * 64, (const GAS float*)k_norm_g + l * 64, lds + RING_BYTES};
;             if (cls && l == 0 && (bx & 1)) asm volatile("s_sleep 127\n\ts_sleep 64" ::: "memory");
;             if (cls && l == 0 && (bx >> 7)) asm volatile("s_sleep 127\n\ts_sleep 127\n\ts_sleep 127" ::: "memory");
;             SW_BEGIN(5);
;             pg8::gemm_phase<pg8::EpiProj>(lds + RING_OFF, g, S, E, sw_acc);
.LBB0_101:
	v_readlane_b32 s0, v252, 3
	v_readlane_b32 s36, v252, 9
	v_readlane_b32 s1, v252, 4
	v_readlane_b32 s37, v252, 10
	v_readlane_b32 s44, v252, 17
	v_readlane_b32 s45, v252, 18
	v_readlane_b32 s46, v252, 19
	v_readlane_b32 s47, v252, 20
	v_readlane_b32 s38, v252, 11
	v_readlane_b32 s39, v252, 12
	v_readlane_b32 s40, v252, 13
	v_readlane_b32 s41, v252, 14
	v_readlane_b32 s42, v252, 15
	v_readlane_b32 s43, v252, 16
	v_readlane_b32 s48, v252, 21
	v_readlane_b32 s49, v252, 22
	v_readlane_b32 s50, v252, 23
	v_readlane_b32 s51, v252, 24
	v_writelane_b32 v250, s0, 0
	v_writelane_b32 v252, s36, 9
	s_nop 0
	v_writelane_b32 v250, s1, 1
	v_readlane_b32 s0, v251, 36
	v_writelane_b32 v252, s37, 10
	v_writelane_b32 v252, s38, 11
	v_writelane_b32 v252, s39, 12
	v_writelane_b32 v252, s40, 13
	v_writelane_b32 v252, s41, 14
	v_writelane_b32 v252, s42, 15
	v_writelane_b32 v252, s43, 16
	v_writelane_b32 v252, s44, 17
	v_writelane_b32 v252, s45, 18
	v_writelane_b32 v252, s46, 19
	v_writelane_b32 v252, s47, 20
	v_writelane_b32 v252, s48, 21
	v_writelane_b32 v252, s49, 22
	v_writelane_b32 v252, s50, 23
	v_writelane_b32 v252, s51, 24
	v_readlane_b32 s1, v251, 37
	s_and_b64 s[4:5], s[0:1], s[6:7]
	v_readlane_b32 s0, v252, 25
	v_readlane_b32 s1, v252, 26
	s_and_b64 s[0:1], s[0:1], s[4:5]
	s_andn2_b64 vcc, exec, s[0:1]
	v_readlane_b32 s0, v252, 5
	v_readlane_b32 s1, v252, 6
	s_nop 0
	v_writelane_b32 v252, s0, 5
	s_nop 1
	v_writelane_b32 v252, s1, 6
	s_cbranch_vccnz .LBB0_103
	s_sleep 96
.LBB0_103:
	v_readlane_b32 s0, v252, 27
	v_readlane_b32 s1, v252, 28
	s_and_b64 s[0:1], s[0:1], s[4:5]
	v_writelane_b32 v250, s6, 2
	s_andn2_b64 vcc, exec, s[0:1]
	s_nop 0
	v_writelane_b32 v250, s7, 3
	s_cbranch_vccnz .LBB0_105
	s_sleep 127
	s_sleep 63
